# fused LN apply: packed sub/mul/fma into final registers, NaN poison via rstd select per row (on top of LN stats rewrite)
# speedup vs baseline: 1.0263x; 1.0003x over previous
; template <unsigned D> __device__ __forceinline__ u32x4 rd8(u32x4 w) { w.x = rd<D>(w.x); w.y = rd<D>(w.y); w.z = rd<D>(w.z); w.w = rd<D>(w.w); return w; }
; __device__ __forceinline__ u32x4 pk8(const f32x4 v0, const f32x4 v1) { u32x4 w; w.x = pk_f16(v0[0], v0[1]); w.y = pk_f16(v0[2], v0[3]); w.z = pk_f16(v1[0], v1[1]); w.w = pk_f16(v1[2], v1[3]); return w; }
; __device__ __forceinline__ unsigned pk4_fp8(float a, float b, float c, float d) { int w = __builtin_amdgcn_cvt_pk_fp8_f32(a, b, 0, false); w = __builtin_amdgcn_cvt_pk_fp8_f32(c, d, w, true); return (unsigned)w; }
;     __device__ __forceinline__ void fused(f32x4 (&acc)[2][2][4][2], const GUnit& u, int wr, int wc, int fr, int fq, LAS unsigned char* lds, int wid, int lane) const {
;     ...
;         const float qnan = __builtin_nanf("");
;         f32x4 gv[2][2], bv[2][2];
; #pragma unroll
;         for (int bj = 0; bj < 2; ++bj)
; #pragma unroll
;             for (int n = 0; n < 2; ++n) { gv[bj][n] = *(const f32x4*)(ln_g + gcol0 + bj * 128 + 4 * n); bv[bj][n] = *(const f32x4*)(ln_b + gcol0 + bj * 128 + 4 * n); }
; #pragma unroll
;         for (int ai = 0; ai < 2; ++ai)
; #pragma unroll
;             for (int m = 0; m < 4; ++m) { const int r = ai * 128 + wr * 64 + m * 16 + fr; const f32x2 sr = S[r]; const size_t row = (size_t)(u.pm * 256 + r);
; #pragma unroll
;                 for (int bj = 0; bj < 2; ++bj) { const int col = gcol0 + bj * 128;
;                     f32x4 y0 = (acc[ai][bj][m][0] - sr.x) * sr.y * gv[bj][0] + bv[bj][0], y1 = (acc[ai][bj][m][1] - sr.x) * sr.y * gv[bj][1] + bv[bj][1];
;                     if (bad) { y0 = (f32x4){qnan, qnan, qnan, qnan}; y1 = y0; }
;                     if (last) { *(f32x4*)(out + row * 1024 + col) = y0; *(f32x4*)(out + row * 1024 + col + 4) = y1; }
;                     else { *(u32x4*)(H16 + row * 1024 + col) = rd8<D_H>(pk8(y0, y1));
;                            if (h8out) { u32x2 q8v; q8v.x = pk4_fp8(y0[0], y0[1], y0[2], y0[3]); q8v.y = pk4_fp8(y1[0], y1[1], y1[2], y1[3]); *(u32x2*)(ws + WS_H8 + row * 1024 + col) = q8v; } } }
.LBB0_470:
	s_or_b64 exec, exec, s[2:3]
	s_lshl_b32 s4, s72, 12
	v_readlane_b32 s2, v255, 9
	v_readlane_b32 s3, v255, 10
	s_add_u32 s2, s2, s4
	s_addc_u32 s3, s3, 0
	v_readlane_b32 s6, v255, 11
	v_readlane_b32 s7, v255, 12
	s_add_u32 s4, s6, s4
	s_addc_u32 s5, s7, 0
	v_lshlrev_b64 v[132:133], 2, v[198:199]
	s_waitcnt lgkmcnt(0)
	s_barrier
	v_lshl_add_u64 v[136:137], s[2:3], 0, v[132:133]
	v_lshl_add_u64 v[144:145], s[4:5], 0, v[132:133]
	global_load_dwordx4 v[156:159], v[144:145], off
	global_load_dwordx4 v[160:163], v[136:137], off
	global_load_dwordx4 v[148:151], v[136:137], off offset:16
	global_load_dwordx4 v[152:155], v[144:145], off offset:16
	s_waitcnt lgkmcnt(1)
	global_load_dwordx4 v[132:135], v[136:137], off offset:528
	global_load_dwordx4 v[140:143], v[136:137], off offset:512
	s_nop 0
	global_load_dwordx4 v[136:139], v[144:145], off offset:528
	s_nop 0
	global_load_dwordx4 v[144:147], v[144:145], off offset:512
	v_lshl_add_u32 v32, v233, 3, 0
	ds_read_b64 v[168:169], v32 offset:8192
	v_readlane_b32 s2, v253, 4
	v_readlane_b32 s3, v253, 5
	s_cmp_lg_u32 s72, 3
	s_mov_b64 s[6:7], -1
	s_waitcnt lgkmcnt(0)
	v_cmp_eq_u32_e64 s[100:101], 0, v170
	s_nop 1
	v_cndmask_b32_e64 v169, v229, v169, s[100:101]
	v_pk_add_f32 v[172:173], v[130:131], v[168:169] op_sel_hi:[1,0] neg_lo:[0,1] neg_hi:[0,1]
	v_pk_add_f32 v[130:131], v[126:127], v[168:169] op_sel_hi:[1,0] neg_lo:[0,1] neg_hi:[0,1]
	v_pk_add_f32 v[174:175], v[128:129], v[168:169] op_sel_hi:[1,0] neg_lo:[0,1] neg_hi:[0,1]
	v_pk_add_f32 v[128:129], v[124:125], v[168:169] op_sel_hi:[1,0] neg_lo:[0,1] neg_hi:[0,1]
	v_pk_mul_f32 v[126:127], v[168:169], v[172:173] op_sel:[1,0]
	v_pk_mul_f32 v[124:125], v[168:169], v[174:175] op_sel:[1,0]
	v_pk_mul_f32 v[130:131], v[168:169], v[130:131] op_sel:[1,0]
	v_pk_mul_f32 v[128:129], v[168:169], v[128:129] op_sel:[1,0]
	v_lshl_add_u64 v[166:167], s[2:3], 0, v[216:217]
	s_cselect_b64 s[2:3], -1, 0
	s_xor_b64 s[4:5], s[26:27], -1
	s_or_b64 s[2:3], s[2:3], s[4:5]
	v_cmp_eq_u32_e64 s[4:5], 0, v170
	v_lshlrev_b64 v[164:165], 10, v[214:215]
	v_lshl_add_u64 v[166:167], v[198:199], 1, v[166:167]
	s_and_b64 vcc, exec, s[2:3]
	s_waitcnt vmcnt(6)
	v_pk_fma_f32 v[126:127], v[162:163], v[126:127], v[158:159]
	v_pk_fma_f32 v[124:125], v[160:161], v[124:125], v[156:157]
	s_waitcnt vmcnt(4)
	v_pk_fma_f32 v[130:131], v[150:151], v[130:131], v[154:155]
	v_pk_fma_f32 v[128:129], v[148:149], v[128:129], v[152:153]
	s_cbranch_vccz .LBB0_474
	v_cvt_pk_f16_f32 v170, v124, v125
	v_cvt_pk_f16_f32 v171, v126, v127
	v_cvt_pk_f16_f32 v172, v128, v129
	v_cvt_pk_f16_f32 v173, v130, v131
	v_add_u32_e32 v170, 0x20002, v170
	v_add_u32_e32 v171, 0x20002, v171
	v_add_u32_e32 v172, 0x20002, v172
	v_add_u32_e32 v173, 0x20002, v173
	v_and_b32_e32 v170, 0xfffcfffc, v170
	v_and_b32_e32 v171, 0xfffcfffc, v171
	v_and_b32_e32 v172, 0xfffcfffc, v172
	v_and_b32_e32 v173, 0xfffcfffc, v173
	s_and_b64 vcc, exec, s[16:17]
	global_store_dwordx4 v[166:167], v[170:173], off
	s_cbranch_vccnz .LBB0_473
	s_nop 0
	v_mov_b32_e32 v170, v33
	v_mov_b32_e32 v171, v33
	v_cvt_pk_fp8_f32 v170, v124, v125
	v_cvt_pk_fp8_f32 v171, v128, v129
	v_readlane_b32 s6, v252, 26
	v_readlane_b32 s7, v252, 27
	v_cvt_pk_fp8_f32 v170, v126, v127 op_sel:[0,0,1]
	v_cvt_pk_fp8_f32 v171, v130, v131 op_sel:[0,0,1]
	v_lshl_add_u64 v[172:173], s[6:7], 0, v[164:165]
	v_lshl_add_u64 v[172:173], v[172:173], 0, v[198:199]
	global_store_dwordx2 v[172:173], v[170:171], off

; template <unsigned D> __device__ __forceinline__ u32x4 rd8(u32x4 w) { w.x = rd<D>(w.x); w.y = rd<D>(w.y); w.z = rd<D>(w.z); w.w = rd<D>(w.w); return w; }
; __device__ __forceinline__ u32x4 pk8(const f32x4 v0, const f32x4 v1) { u32x4 w; w.x = pk_f16(v0[0], v0[1]); w.y = pk_f16(v0[2], v0[3]); w.z = pk_f16(v1[0], v1[1]); w.w = pk_f16(v1[2], v1[3]); return w; }
; __device__ __forceinline__ unsigned pk4_fp8(float a, float b, float c, float d) { int w = __builtin_amdgcn_cvt_pk_fp8_f32(a, b, 0, false); w = __builtin_amdgcn_cvt_pk_fp8_f32(c, d, w, true); return (unsigned)w; }
;     __device__ __forceinline__ void fused(f32x4 (&acc)[2][2][4][2], const GUnit& u, int wr, int wc, int fr, int fq, LAS unsigned char* lds, int wid, int lane) const {
;     ...
;             for (int m = 0; m < 4; ++m) { const int r = ai * 128 + wr * 64 + m * 16 + fr; const f32x2 sr = S[r]; const size_t row = (size_t)(u.pm * 256 + r);
; #pragma unroll
;                 for (int bj = 0; bj < 2; ++bj) { const int col = gcol0 + bj * 128;
;                     f32x4 y0 = (acc[ai][bj][m][0] - sr.x) * sr.y * gv[bj][0] + bv[bj][0], y1 = (acc[ai][bj][m][1] - sr.x) * sr.y * gv[bj][1] + bv[bj][1];
;                     if (bad) { y0 = (f32x4){qnan, qnan, qnan, qnan}; y1 = y0; }
;                     if (last) { *(f32x4*)(out + row * 1024 + col) = y0; *(f32x4*)(out + row * 1024 + col + 4) = y1; }
;                     else { *(u32x4*)(H16 + row * 1024 + col) = rd8<D_H>(pk8(y0, y1));
;                            if (h8out) { u32x2 q8v; q8v.x = pk4_fp8(y0[0], y0[1], y0[2], y0[3]); q8v.y = pk4_fp8(y1[0], y1[1], y1[2], y1[3]); *(u32x2*)(ws + WS_H8 + row * 1024 + col) = q8v; } } }
.LBB0_476:
	s_nop 0
	v_pk_add_f32 v[124:125], v[120:121], v[168:169] op_sel_hi:[1,0] neg_lo:[0,1] neg_hi:[0,1]
	v_pk_add_f32 v[120:121], v[116:117], v[168:169] op_sel_hi:[1,0] neg_lo:[0,1] neg_hi:[0,1]
	v_pk_add_f32 v[126:127], v[122:123], v[168:169] op_sel_hi:[1,0] neg_lo:[0,1] neg_hi:[0,1]
	v_pk_add_f32 v[122:123], v[118:119], v[168:169] op_sel_hi:[1,0] neg_lo:[0,1] neg_hi:[0,1]
	v_pk_mul_f32 v[116:117], v[168:169], v[124:125] op_sel:[1,0]
	v_pk_mul_f32 v[118:119], v[168:169], v[126:127] op_sel:[1,0]
	v_pk_mul_f32 v[120:121], v[168:169], v[120:121] op_sel:[1,0]
	v_pk_mul_f32 v[122:123], v[168:169], v[122:123] op_sel:[1,0]
	s_waitcnt vmcnt(0)
	v_pk_fma_f32 v[116:117], v[140:141], v[116:117], v[144:145]
	v_pk_fma_f32 v[118:119], v[142:143], v[118:119], v[146:147]
	v_pk_fma_f32 v[120:121], v[132:133], v[120:121], v[136:137]
	v_pk_fma_f32 v[122:123], v[134:135], v[122:123], v[138:139]
	s_mov_b64 s[6:7], -1
	s_and_b64 vcc, exec, s[2:3]
	s_cbranch_vccz .LBB0_480
	v_cvt_pk_f16_f32 v124, v116, v117
	v_cvt_pk_f16_f32 v125, v118, v119
	v_cvt_pk_f16_f32 v126, v120, v121
	v_cvt_pk_f16_f32 v127, v122, v123
	v_add_u32_e32 v124, 0x20002, v124
	v_add_u32_e32 v125, 0x20002, v125
	v_add_u32_e32 v126, 0x20002, v126
	v_add_u32_e32 v127, 0x20002, v127
	v_and_b32_e32 v124, 0xfffcfffc, v124
	v_and_b32_e32 v125, 0xfffcfffc, v125
	v_and_b32_e32 v126, 0xfffcfffc, v126
	v_and_b32_e32 v127, 0xfffcfffc, v127
	s_and_b64 vcc, exec, s[16:17]
	global_store_dwordx4 v[166:167], v[124:127], off offset:256
	s_cbranch_vccnz .LBB0_479
	s_nop 0
	v_mov_b32_e32 v124, v33
	v_mov_b32_e32 v125, v33
	v_cvt_pk_fp8_f32 v124, v116, v117
	v_cvt_pk_fp8_f32 v125, v120, v121
	v_readlane_b32 s6, v252, 26
	v_readlane_b32 s7, v252, 27
	v_cvt_pk_fp8_f32 v124, v118, v119 op_sel:[0,0,1]
	v_cvt_pk_fp8_f32 v125, v122, v123 op_sel:[0,0,1]
	v_lshl_add_u64 v[126:127], s[6:7], 0, v[164:165]
	v_lshl_add_u64 v[126:127], v[126:127], 0, v[198:199]
	global_store_dwordx2 v[126:127], v[124:125], off offset:128

; template <unsigned D> __device__ __forceinline__ u32x4 rd8(u32x4 w) { w.x = rd<D>(w.x); w.y = rd<D>(w.y); w.z = rd<D>(w.z); w.w = rd<D>(w.w); return w; }
; __device__ __forceinline__ u32x4 pk8(const f32x4 v0, const f32x4 v1) { u32x4 w; w.x = pk_f16(v0[0], v0[1]); w.y = pk_f16(v0[2], v0[3]); w.z = pk_f16(v1[0], v1[1]); w.w = pk_f16(v1[2], v1[3]); return w; }
; __device__ __forceinline__ unsigned pk4_fp8(float a, float b, float c, float d) { int w = __builtin_amdgcn_cvt_pk_fp8_f32(a, b, 0, false); w = __builtin_amdgcn_cvt_pk_fp8_f32(c, d, w, true); return (unsigned)w; }
;     __device__ __forceinline__ void fused(f32x4 (&acc)[2][2][4][2], const GUnit& u, int wr, int wc, int fr, int fq, LAS unsigned char* lds, int wid, int lane) const {
;     ...
;             for (int m = 0; m < 4; ++m) { const int r = ai * 128 + wr * 64 + m * 16 + fr; const f32x2 sr = S[r]; const size_t row = (size_t)(u.pm * 256 + r);
; #pragma unroll
;                 for (int bj = 0; bj < 2; ++bj) { const int col = gcol0 + bj * 128;
;                     f32x4 y0 = (acc[ai][bj][m][0] - sr.x) * sr.y * gv[bj][0] + bv[bj][0], y1 = (acc[ai][bj][m][1] - sr.x) * sr.y * gv[bj][1] + bv[bj][1];
;                     if (bad) { y0 = (f32x4){qnan, qnan, qnan, qnan}; y1 = y0; }
;                     if (last) { *(f32x4*)(out + row * 1024 + col) = y0; *(f32x4*)(out + row * 1024 + col + 4) = y1; }
;                     else { *(u32x4*)(H16 + row * 1024 + col) = rd8<D_H>(pk8(y0, y1));
;                            if (h8out) { u32x2 q8v; q8v.x = pk4_fp8(y0[0], y0[1], y0[2], y0[3]); q8v.y = pk4_fp8(y1[0], y1[1], y1[2], y1[3]); *(u32x2*)(ws + WS_H8 + row * 1024 + col) = q8v; } } }
.LBB0_482:
	ds_read_b64 v[118:119], v32 offset:8320
	s_nop 0
	v_add3_u32 v120, s14, v233, 16
	v_ashrrev_i32_e32 v121, 31, v120
	v_readlane_b32 s6, v253, 4
	v_lshlrev_b64 v[116:117], 10, v[120:121]
	s_waitcnt lgkmcnt(0)
	v_cndmask_b32_e64 v119, v229, v119, s[100:101]
	v_pk_add_f32 v[122:123], v[112:113], v[118:119] op_sel_hi:[1,0] neg_lo:[0,1] neg_hi:[0,1]
	v_pk_add_f32 v[112:113], v[108:109], v[118:119] op_sel_hi:[1,0] neg_lo:[0,1] neg_hi:[0,1]
	v_pk_add_f32 v[124:125], v[114:115], v[118:119] op_sel_hi:[1,0] neg_lo:[0,1] neg_hi:[0,1]
	v_pk_add_f32 v[114:115], v[110:111], v[118:119] op_sel_hi:[1,0] neg_lo:[0,1] neg_hi:[0,1]
	v_pk_mul_f32 v[108:109], v[118:119], v[122:123] op_sel:[1,0]
	v_pk_mul_f32 v[110:111], v[118:119], v[124:125] op_sel:[1,0]
	v_pk_mul_f32 v[112:113], v[118:119], v[112:113] op_sel:[1,0]
	v_pk_mul_f32 v[114:115], v[118:119], v[114:115] op_sel:[1,0]
	v_lshlrev_b64 v[120:121], 11, v[120:121]
	v_readlane_b32 s7, v253, 5
	v_lshl_add_u64 v[120:121], s[6:7], 0, v[120:121]
	v_pk_fma_f32 v[108:109], v[160:161], v[108:109], v[156:157]
	v_pk_fma_f32 v[110:111], v[162:163], v[110:111], v[158:159]
	v_pk_fma_f32 v[112:113], v[148:149], v[112:113], v[152:153]
	v_pk_fma_f32 v[114:115], v[150:151], v[114:115], v[154:155]
	s_mov_b64 s[6:7], -1
	s_and_b64 vcc, exec, s[2:3]
	v_lshl_add_u64 v[120:121], v[198:199], 1, v[120:121]
	s_cbranch_vccz .LBB0_486
	v_cvt_pk_f16_f32 v122, v108, v109
	v_cvt_pk_f16_f32 v123, v110, v111
	v_cvt_pk_f16_f32 v124, v112, v113
	v_cvt_pk_f16_f32 v125, v114, v115
	v_add_u32_e32 v122, 0x20002, v122
	v_add_u32_e32 v123, 0x20002, v123
	v_add_u32_e32 v124, 0x20002, v124
	v_add_u32_e32 v125, 0x20002, v125
	v_and_b32_e32 v122, 0xfffcfffc, v122
	v_and_b32_e32 v123, 0xfffcfffc, v123
	v_and_b32_e32 v124, 0xfffcfffc, v124
	v_and_b32_e32 v125, 0xfffcfffc, v125
	s_and_b64 vcc, exec, s[16:17]
	global_store_dwordx4 v[120:121], v[122:125], off
	s_cbranch_vccnz .LBB0_485
	s_nop 0
	v_mov_b32_e32 v122, v33
	v_mov_b32_e32 v123, v33
	v_cvt_pk_fp8_f32 v122, v108, v109
	v_cvt_pk_fp8_f32 v123, v112, v113
	v_readlane_b32 s6, v252, 26
	v_readlane_b32 s7, v252, 27
	v_cvt_pk_fp8_f32 v122, v110, v111 op_sel:[0,0,1]
	v_cvt_pk_fp8_f32 v123, v114, v115 op_sel:[0,0,1]
	v_lshl_add_u64 v[124:125], s[6:7], 0, v[116:117]
	v_lshl_add_u64 v[124:125], v[124:125], 0, v[198:199]
	global_store_dwordx2 v[124:125], v[122:123], off

; template <unsigned D> __device__ __forceinline__ u32x4 rd8(u32x4 w) { w.x = rd<D>(w.x); w.y = rd<D>(w.y); w.z = rd<D>(w.z); w.w = rd<D>(w.w); return w; }
; __device__ __forceinline__ u32x4 pk8(const f32x4 v0, const f32x4 v1) { u32x4 w; w.x = pk_f16(v0[0], v0[1]); w.y = pk_f16(v0[2], v0[3]); w.z = pk_f16(v1[0], v1[1]); w.w = pk_f16(v1[2], v1[3]); return w; }
; __device__ __forceinline__ unsigned pk4_fp8(float a, float b, float c, float d) { int w = __builtin_amdgcn_cvt_pk_fp8_f32(a, b, 0, false); w = __builtin_amdgcn_cvt_pk_fp8_f32(c, d, w, true); return (unsigned)w; }
;     __device__ __forceinline__ void fused(f32x4 (&acc)[2][2][4][2], const GUnit& u, int wr, int wc, int fr, int fq, LAS unsigned char* lds, int wid, int lane) const {
;     ...
;             for (int m = 0; m < 4; ++m) { const int r = ai * 128 + wr * 64 + m * 16 + fr; const f32x2 sr = S[r]; const size_t row = (size_t)(u.pm * 256 + r);
; #pragma unroll
;                 for (int bj = 0; bj < 2; ++bj) { const int col = gcol0 + bj * 128;
;                     f32x4 y0 = (acc[ai][bj][m][0] - sr.x) * sr.y * gv[bj][0] + bv[bj][0], y1 = (acc[ai][bj][m][1] - sr.x) * sr.y * gv[bj][1] + bv[bj][1];
;                     if (bad) { y0 = (f32x4){qnan, qnan, qnan, qnan}; y1 = y0; }
;                     if (last) { *(f32x4*)(out + row * 1024 + col) = y0; *(f32x4*)(out + row * 1024 + col + 4) = y1; }
;                     else { *(u32x4*)(H16 + row * 1024 + col) = rd8<D_H>(pk8(y0, y1));
;                            if (h8out) { u32x2 q8v; q8v.x = pk4_fp8(y0[0], y0[1], y0[2], y0[3]); q8v.y = pk4_fp8(y1[0], y1[1], y1[2], y1[3]); *(u32x2*)(ws + WS_H8 + row * 1024 + col) = q8v; } } }
.LBB0_488:
	s_nop 0
	v_pk_add_f32 v[108:109], v[104:105], v[118:119] op_sel_hi:[1,0] neg_lo:[0,1] neg_hi:[0,1]
	v_pk_add_f32 v[104:105], v[100:101], v[118:119] op_sel_hi:[1,0] neg_lo:[0,1] neg_hi:[0,1]
	v_pk_add_f32 v[110:111], v[106:107], v[118:119] op_sel_hi:[1,0] neg_lo:[0,1] neg_hi:[0,1]
	v_pk_add_f32 v[106:107], v[102:103], v[118:119] op_sel_hi:[1,0] neg_lo:[0,1] neg_hi:[0,1]
	v_pk_mul_f32 v[100:101], v[118:119], v[108:109] op_sel:[1,0]
	v_pk_mul_f32 v[102:103], v[118:119], v[110:111] op_sel:[1,0]
	v_pk_mul_f32 v[104:105], v[118:119], v[104:105] op_sel:[1,0]
	v_pk_mul_f32 v[106:107], v[118:119], v[106:107] op_sel:[1,0]
	v_pk_fma_f32 v[100:101], v[140:141], v[100:101], v[144:145]
	v_pk_fma_f32 v[102:103], v[142:143], v[102:103], v[146:147]
	v_pk_fma_f32 v[104:105], v[132:133], v[104:105], v[136:137]
	v_pk_fma_f32 v[106:107], v[134:135], v[106:107], v[138:139]
	s_mov_b64 s[6:7], -1
	s_and_b64 vcc, exec, s[2:3]
	s_cbranch_vccz .LBB0_492
	v_cvt_pk_f16_f32 v108, v100, v101
	v_cvt_pk_f16_f32 v109, v102, v103
	v_cvt_pk_f16_f32 v110, v104, v105
	v_cvt_pk_f16_f32 v111, v106, v107
	v_add_u32_e32 v108, 0x20002, v108
	v_add_u32_e32 v109, 0x20002, v109
	v_add_u32_e32 v110, 0x20002, v110
	v_add_u32_e32 v111, 0x20002, v111
	v_and_b32_e32 v108, 0xfffcfffc, v108
	v_and_b32_e32 v109, 0xfffcfffc, v109
	v_and_b32_e32 v110, 0xfffcfffc, v110
	v_and_b32_e32 v111, 0xfffcfffc, v111
	s_and_b64 vcc, exec, s[16:17]
	global_store_dwordx4 v[120:121], v[108:111], off offset:256
	s_cbranch_vccnz .LBB0_491
	s_nop 0
	v_mov_b32_e32 v108, v33
	v_mov_b32_e32 v109, v33
	v_cvt_pk_fp8_f32 v108, v100, v101
	v_cvt_pk_fp8_f32 v109, v104, v105
	v_readlane_b32 s6, v252, 26
	v_readlane_b32 s7, v252, 27
	v_cvt_pk_fp8_f32 v108, v102, v103 op_sel:[0,0,1]
	v_cvt_pk_fp8_f32 v109, v106, v107 op_sel:[0,0,1]
	v_lshl_add_u64 v[110:111], s[6:7], 0, v[116:117]
	v_lshl_add_u64 v[110:111], v[110:111], 0, v[198:199]
	global_store_dwordx2 v[110:111], v[108:109], off offset:128

; template <unsigned D> __device__ __forceinline__ u32x4 rd8(u32x4 w) { w.x = rd<D>(w.x); w.y = rd<D>(w.y); w.z = rd<D>(w.z); w.w = rd<D>(w.w); return w; }
; __device__ __forceinline__ u32x4 pk8(const f32x4 v0, const f32x4 v1) { u32x4 w; w.x = pk_f16(v0[0], v0[1]); w.y = pk_f16(v0[2], v0[3]); w.z = pk_f16(v1[0], v1[1]); w.w = pk_f16(v1[2], v1[3]); return w; }
; __device__ __forceinline__ unsigned pk4_fp8(float a, float b, float c, float d) { int w = __builtin_amdgcn_cvt_pk_fp8_f32(a, b, 0, false); w = __builtin_amdgcn_cvt_pk_fp8_f32(c, d, w, true); return (unsigned)w; }
;     __device__ __forceinline__ void fused(f32x4 (&acc)[2][2][4][2], const GUnit& u, int wr, int wc, int fr, int fq, LAS unsigned char* lds, int wid, int lane) const {
;     ...
;             for (int m = 0; m < 4; ++m) { const int r = ai * 128 + wr * 64 + m * 16 + fr; const f32x2 sr = S[r]; const size_t row = (size_t)(u.pm * 256 + r);
; #pragma unroll
;                 for (int bj = 0; bj < 2; ++bj) { const int col = gcol0 + bj * 128;
;                     f32x4 y0 = (acc[ai][bj][m][0] - sr.x) * sr.y * gv[bj][0] + bv[bj][0], y1 = (acc[ai][bj][m][1] - sr.x) * sr.y * gv[bj][1] + bv[bj][1];
;                     if (bad) { y0 = (f32x4){qnan, qnan, qnan, qnan}; y1 = y0; }
;                     if (last) { *(f32x4*)(out + row * 1024 + col) = y0; *(f32x4*)(out + row * 1024 + col + 4) = y1; }
;                     else { *(u32x4*)(H16 + row * 1024 + col) = rd8<D_H>(pk8(y0, y1));
;                            if (h8out) { u32x2 q8v; q8v.x = pk4_fp8(y0[0], y0[1], y0[2], y0[3]); q8v.y = pk4_fp8(y1[0], y1[1], y1[2], y1[3]); *(u32x2*)(ws + WS_H8 + row * 1024 + col) = q8v; } } }
.LBB0_494:
	ds_read_b64 v[102:103], v32 offset:8448
	s_nop 0
	v_add3_u32 v104, s14, v233, 32
	v_ashrrev_i32_e32 v105, 31, v104
	v_readlane_b32 s6, v253, 4
	v_lshlrev_b64 v[100:101], 10, v[104:105]
	s_waitcnt lgkmcnt(0)
	v_cndmask_b32_e64 v103, v229, v103, s[100:101]
	v_pk_add_f32 v[106:107], v[96:97], v[102:103] op_sel_hi:[1,0] neg_lo:[0,1] neg_hi:[0,1]
	v_pk_add_f32 v[96:97], v[92:93], v[102:103] op_sel_hi:[1,0] neg_lo:[0,1] neg_hi:[0,1]
	v_pk_add_f32 v[108:109], v[98:99], v[102:103] op_sel_hi:[1,0] neg_lo:[0,1] neg_hi:[0,1]
	v_pk_add_f32 v[98:99], v[94:95], v[102:103] op_sel_hi:[1,0] neg_lo:[0,1] neg_hi:[0,1]
	v_pk_mul_f32 v[92:93], v[102:103], v[106:107] op_sel:[1,0]
	v_pk_mul_f32 v[94:95], v[102:103], v[108:109] op_sel:[1,0]
	v_pk_mul_f32 v[96:97], v[102:103], v[96:97] op_sel:[1,0]
	v_pk_mul_f32 v[98:99], v[102:103], v[98:99] op_sel:[1,0]
	v_lshlrev_b64 v[104:105], 11, v[104:105]
	v_readlane_b32 s7, v253, 5
	v_lshl_add_u64 v[104:105], s[6:7], 0, v[104:105]
	v_pk_fma_f32 v[92:93], v[160:161], v[92:93], v[156:157]
	v_pk_fma_f32 v[94:95], v[162:163], v[94:95], v[158:159]
	v_pk_fma_f32 v[96:97], v[148:149], v[96:97], v[152:153]
	v_pk_fma_f32 v[98:99], v[150:151], v[98:99], v[154:155]
	s_mov_b64 s[6:7], -1
	s_and_b64 vcc, exec, s[2:3]
	v_lshl_add_u64 v[104:105], v[198:199], 1, v[104:105]
	s_cbranch_vccz .LBB0_498
	v_cvt_pk_f16_f32 v106, v92, v93
	v_cvt_pk_f16_f32 v107, v94, v95
	v_cvt_pk_f16_f32 v108, v96, v97
	v_cvt_pk_f16_f32 v109, v98, v99
	v_add_u32_e32 v106, 0x20002, v106
	v_add_u32_e32 v107, 0x20002, v107
	v_add_u32_e32 v108, 0x20002, v108
	v_add_u32_e32 v109, 0x20002, v109
	v_and_b32_e32 v106, 0xfffcfffc, v106
	v_and_b32_e32 v107, 0xfffcfffc, v107
	v_and_b32_e32 v108, 0xfffcfffc, v108
	v_and_b32_e32 v109, 0xfffcfffc, v109
	s_and_b64 vcc, exec, s[16:17]
	global_store_dwordx4 v[104:105], v[106:109], off
	s_cbranch_vccnz .LBB0_497
	s_nop 0
	v_mov_b32_e32 v106, v33
	v_mov_b32_e32 v107, v33
	v_cvt_pk_fp8_f32 v106, v92, v93
	v_cvt_pk_fp8_f32 v107, v96, v97
	v_readlane_b32 s6, v252, 26
	v_readlane_b32 s7, v252, 27
	v_cvt_pk_fp8_f32 v106, v94, v95 op_sel:[0,0,1]
	v_cvt_pk_fp8_f32 v107, v98, v99 op_sel:[0,0,1]
	v_lshl_add_u64 v[108:109], s[6:7], 0, v[100:101]
	v_lshl_add_u64 v[108:109], v[108:109], 0, v[198:199]
	global_store_dwordx2 v[108:109], v[106:107], off

; template <unsigned D> __device__ __forceinline__ u32x4 rd8(u32x4 w) { w.x = rd<D>(w.x); w.y = rd<D>(w.y); w.z = rd<D>(w.z); w.w = rd<D>(w.w); return w; }
; __device__ __forceinline__ u32x4 pk8(const f32x4 v0, const f32x4 v1) { u32x4 w; w.x = pk_f16(v0[0], v0[1]); w.y = pk_f16(v0[2], v0[3]); w.z = pk_f16(v1[0], v1[1]); w.w = pk_f16(v1[2], v1[3]); return w; }
; __device__ __forceinline__ unsigned pk4_fp8(float a, float b, float c, float d) { int w = __builtin_amdgcn_cvt_pk_fp8_f32(a, b, 0, false); w = __builtin_amdgcn_cvt_pk_fp8_f32(c, d, w, true); return (unsigned)w; }
;     __device__ __forceinline__ void fused(f32x4 (&acc)[2][2][4][2], const GUnit& u, int wr, int wc, int fr, int fq, LAS unsigned char* lds, int wid, int lane) const {
;     ...
;             for (int m = 0; m < 4; ++m) { const int r = ai * 128 + wr * 64 + m * 16 + fr; const f32x2 sr = S[r]; const size_t row = (size_t)(u.pm * 256 + r);
; #pragma unroll
;                 for (int bj = 0; bj < 2; ++bj) { const int col = gcol0 + bj * 128;
;                     f32x4 y0 = (acc[ai][bj][m][0] - sr.x) * sr.y * gv[bj][0] + bv[bj][0], y1 = (acc[ai][bj][m][1] - sr.x) * sr.y * gv[bj][1] + bv[bj][1];
;                     if (bad) { y0 = (f32x4){qnan, qnan, qnan, qnan}; y1 = y0; }
;                     if (last) { *(f32x4*)(out + row * 1024 + col) = y0; *(f32x4*)(out + row * 1024 + col + 4) = y1; }
;                     else { *(u32x4*)(H16 + row * 1024 + col) = rd8<D_H>(pk8(y0, y1));
;                            if (h8out) { u32x2 q8v; q8v.x = pk4_fp8(y0[0], y0[1], y0[2], y0[3]); q8v.y = pk4_fp8(y1[0], y1[1], y1[2], y1[3]); *(u32x2*)(ws + WS_H8 + row * 1024 + col) = q8v; } } }
.LBB0_500:
	s_nop 0
	v_pk_add_f32 v[92:93], v[88:89], v[102:103] op_sel_hi:[1,0] neg_lo:[0,1] neg_hi:[0,1]
	v_pk_add_f32 v[88:89], v[84:85], v[102:103] op_sel_hi:[1,0] neg_lo:[0,1] neg_hi:[0,1]
	v_pk_add_f32 v[94:95], v[90:91], v[102:103] op_sel_hi:[1,0] neg_lo:[0,1] neg_hi:[0,1]
	v_pk_add_f32 v[90:91], v[86:87], v[102:103] op_sel_hi:[1,0] neg_lo:[0,1] neg_hi:[0,1]
	v_pk_mul_f32 v[84:85], v[102:103], v[92:93] op_sel:[1,0]
	v_pk_mul_f32 v[86:87], v[102:103], v[94:95] op_sel:[1,0]
	v_pk_mul_f32 v[88:89], v[102:103], v[88:89] op_sel:[1,0]
	v_pk_mul_f32 v[90:91], v[102:103], v[90:91] op_sel:[1,0]
	v_pk_fma_f32 v[84:85], v[140:141], v[84:85], v[144:145]
	v_pk_fma_f32 v[86:87], v[142:143], v[86:87], v[146:147]
	v_pk_fma_f32 v[88:89], v[132:133], v[88:89], v[136:137]
	v_pk_fma_f32 v[90:91], v[134:135], v[90:91], v[138:139]
	s_mov_b64 s[6:7], -1
	s_and_b64 vcc, exec, s[2:3]
	s_cbranch_vccz .LBB0_504
	v_cvt_pk_f16_f32 v92, v84, v85
	v_cvt_pk_f16_f32 v93, v86, v87
	v_cvt_pk_f16_f32 v94, v88, v89
	v_cvt_pk_f16_f32 v95, v90, v91
	v_add_u32_e32 v92, 0x20002, v92
	v_add_u32_e32 v93, 0x20002, v93
	v_add_u32_e32 v94, 0x20002, v94
	v_add_u32_e32 v95, 0x20002, v95
	v_and_b32_e32 v92, 0xfffcfffc, v92
	v_and_b32_e32 v93, 0xfffcfffc, v93
	v_and_b32_e32 v94, 0xfffcfffc, v94
	v_and_b32_e32 v95, 0xfffcfffc, v95
	s_and_b64 vcc, exec, s[16:17]
	global_store_dwordx4 v[104:105], v[92:95], off offset:256
	s_cbranch_vccnz .LBB0_503
	s_nop 0
	v_mov_b32_e32 v92, v33
	v_mov_b32_e32 v93, v33
	v_cvt_pk_fp8_f32 v92, v84, v85
	v_cvt_pk_fp8_f32 v93, v88, v89
	v_readlane_b32 s6, v252, 26
	v_readlane_b32 s7, v252, 27
	v_cvt_pk_fp8_f32 v92, v86, v87 op_sel:[0,0,1]
	v_cvt_pk_fp8_f32 v93, v90, v91 op_sel:[0,0,1]
	v_lshl_add_u64 v[94:95], s[6:7], 0, v[100:101]
	v_lshl_add_u64 v[94:95], v[94:95], 0, v[198:199]
	global_store_dwordx2 v[94:95], v[92:93], off offset:128

; template <unsigned D> __device__ __forceinline__ u32x4 rd8(u32x4 w) { w.x = rd<D>(w.x); w.y = rd<D>(w.y); w.z = rd<D>(w.z); w.w = rd<D>(w.w); return w; }
; __device__ __forceinline__ u32x4 pk8(const f32x4 v0, const f32x4 v1) { u32x4 w; w.x = pk_f16(v0[0], v0[1]); w.y = pk_f16(v0[2], v0[3]); w.z = pk_f16(v1[0], v1[1]); w.w = pk_f16(v1[2], v1[3]); return w; }
; __device__ __forceinline__ unsigned pk4_fp8(float a, float b, float c, float d) { int w = __builtin_amdgcn_cvt_pk_fp8_f32(a, b, 0, false); w = __builtin_amdgcn_cvt_pk_fp8_f32(c, d, w, true); return (unsigned)w; }
;     __device__ __forceinline__ void fused(f32x4 (&acc)[2][2][4][2], const GUnit& u, int wr, int wc, int fr, int fq, LAS unsigned char* lds, int wid, int lane) const {
;     ...
;             for (int m = 0; m < 4; ++m) { const int r = ai * 128 + wr * 64 + m * 16 + fr; const f32x2 sr = S[r]; const size_t row = (size_t)(u.pm * 256 + r);
; #pragma unroll
;                 for (int bj = 0; bj < 2; ++bj) { const int col = gcol0 + bj * 128;
;                     f32x4 y0 = (acc[ai][bj][m][0] - sr.x) * sr.y * gv[bj][0] + bv[bj][0], y1 = (acc[ai][bj][m][1] - sr.x) * sr.y * gv[bj][1] + bv[bj][1];
;                     if (bad) { y0 = (f32x4){qnan, qnan, qnan, qnan}; y1 = y0; }
;                     if (last) { *(f32x4*)(out + row * 1024 + col) = y0; *(f32x4*)(out + row * 1024 + col + 4) = y1; }
;                     else { *(u32x4*)(H16 + row * 1024 + col) = rd8<D_H>(pk8(y0, y1));
;                            if (h8out) { u32x2 q8v; q8v.x = pk4_fp8(y0[0], y0[1], y0[2], y0[3]); q8v.y = pk4_fp8(y1[0], y1[1], y1[2], y1[3]); *(u32x2*)(ws + WS_H8 + row * 1024 + col) = q8v; } } }
.LBB0_506:
	ds_read_b64 v[86:87], v32 offset:8576
	s_nop 0
	v_add3_u32 v88, s14, v233, 48
	v_ashrrev_i32_e32 v89, 31, v88
	v_readlane_b32 s6, v253, 4
	v_lshlrev_b64 v[84:85], 10, v[88:89]
	s_waitcnt lgkmcnt(0)
	v_cndmask_b32_e64 v87, v229, v87, s[100:101]
	v_pk_add_f32 v[90:91], v[80:81], v[86:87] op_sel_hi:[1,0] neg_lo:[0,1] neg_hi:[0,1]
	v_pk_add_f32 v[80:81], v[76:77], v[86:87] op_sel_hi:[1,0] neg_lo:[0,1] neg_hi:[0,1]
	v_pk_add_f32 v[92:93], v[82:83], v[86:87] op_sel_hi:[1,0] neg_lo:[0,1] neg_hi:[0,1]
	v_pk_add_f32 v[82:83], v[78:79], v[86:87] op_sel_hi:[1,0] neg_lo:[0,1] neg_hi:[0,1]
	v_pk_mul_f32 v[76:77], v[86:87], v[90:91] op_sel:[1,0]
	v_pk_mul_f32 v[78:79], v[86:87], v[92:93] op_sel:[1,0]
	v_pk_mul_f32 v[80:81], v[86:87], v[80:81] op_sel:[1,0]
	v_pk_mul_f32 v[82:83], v[86:87], v[82:83] op_sel:[1,0]
	v_lshlrev_b64 v[88:89], 11, v[88:89]
	v_readlane_b32 s7, v253, 5
	v_lshl_add_u64 v[88:89], s[6:7], 0, v[88:89]
	v_pk_fma_f32 v[76:77], v[160:161], v[76:77], v[156:157]
	v_pk_fma_f32 v[78:79], v[162:163], v[78:79], v[158:159]
	v_pk_fma_f32 v[80:81], v[148:149], v[80:81], v[152:153]
	v_pk_fma_f32 v[82:83], v[150:151], v[82:83], v[154:155]
	s_mov_b64 s[6:7], -1
	s_and_b64 vcc, exec, s[2:3]
	v_lshl_add_u64 v[88:89], v[198:199], 1, v[88:89]
	v_mov_b32_e32 v233, v226
	s_cbranch_vccz .LBB0_510
	v_cvt_pk_f16_f32 v90, v76, v77
	v_cvt_pk_f16_f32 v91, v78, v79
	v_cvt_pk_f16_f32 v92, v80, v81
	v_cvt_pk_f16_f32 v93, v82, v83
	v_add_u32_e32 v90, 0x20002, v90
	v_add_u32_e32 v91, 0x20002, v91
	v_add_u32_e32 v92, 0x20002, v92
	v_add_u32_e32 v93, 0x20002, v93
	v_and_b32_e32 v90, 0xfffcfffc, v90
	v_and_b32_e32 v91, 0xfffcfffc, v91
	v_and_b32_e32 v92, 0xfffcfffc, v92
	v_and_b32_e32 v93, 0xfffcfffc, v93
	s_and_b64 vcc, exec, s[16:17]
	global_store_dwordx4 v[88:89], v[90:93], off
	s_cbranch_vccnz .LBB0_509
	s_nop 0
	v_mov_b32_e32 v90, v33
	v_mov_b32_e32 v91, v33
	v_cvt_pk_fp8_f32 v90, v76, v77
	v_cvt_pk_fp8_f32 v91, v80, v81
	v_readlane_b32 s6, v252, 26
	v_readlane_b32 s7, v252, 27
	v_cvt_pk_fp8_f32 v90, v78, v79 op_sel:[0,0,1]
	v_cvt_pk_fp8_f32 v91, v82, v83 op_sel:[0,0,1]
	v_lshl_add_u64 v[92:93], s[6:7], 0, v[84:85]
	v_lshl_add_u64 v[92:93], v[92:93], 0, v[198:199]
	global_store_dwordx2 v[92:93], v[90:91], off

; template <unsigned D> __device__ __forceinline__ u32x4 rd8(u32x4 w) { w.x = rd<D>(w.x); w.y = rd<D>(w.y); w.z = rd<D>(w.z); w.w = rd<D>(w.w); return w; }
; __device__ __forceinline__ u32x4 pk8(const f32x4 v0, const f32x4 v1) { u32x4 w; w.x = pk_f16(v0[0], v0[1]); w.y = pk_f16(v0[2], v0[3]); w.z = pk_f16(v1[0], v1[1]); w.w = pk_f16(v1[2], v1[3]); return w; }
; __device__ __forceinline__ unsigned pk4_fp8(float a, float b, float c, float d) { int w = __builtin_amdgcn_cvt_pk_fp8_f32(a, b, 0, false); w = __builtin_amdgcn_cvt_pk_fp8_f32(c, d, w, true); return (unsigned)w; }
;     __device__ __forceinline__ void fused(f32x4 (&acc)[2][2][4][2], const GUnit& u, int wr, int wc, int fr, int fq, LAS unsigned char* lds, int wid, int lane) const {
;     ...
;             for (int m = 0; m < 4; ++m) { const int r = ai * 128 + wr * 64 + m * 16 + fr; const f32x2 sr = S[r]; const size_t row = (size_t)(u.pm * 256 + r);
; #pragma unroll
;                 for (int bj = 0; bj < 2; ++bj) { const int col = gcol0 + bj * 128;
;                     f32x4 y0 = (acc[ai][bj][m][0] - sr.x) * sr.y * gv[bj][0] + bv[bj][0], y1 = (acc[ai][bj][m][1] - sr.x) * sr.y * gv[bj][1] + bv[bj][1];
;                     if (bad) { y0 = (f32x4){qnan, qnan, qnan, qnan}; y1 = y0; }
;                     if (last) { *(f32x4*)(out + row * 1024 + col) = y0; *(f32x4*)(out + row * 1024 + col + 4) = y1; }
;                     else { *(u32x4*)(H16 + row * 1024 + col) = rd8<D_H>(pk8(y0, y1));
;                            if (h8out) { u32x2 q8v; q8v.x = pk4_fp8(y0[0], y0[1], y0[2], y0[3]); q8v.y = pk4_fp8(y1[0], y1[1], y1[2], y1[3]); *(u32x2*)(ws + WS_H8 + row * 1024 + col) = q8v; } } }
.LBB0_512:
	s_nop 0
	v_pk_add_f32 v[76:77], v[72:73], v[86:87] op_sel_hi:[1,0] neg_lo:[0,1] neg_hi:[0,1]
	v_pk_add_f32 v[72:73], v[68:69], v[86:87] op_sel_hi:[1,0] neg_lo:[0,1] neg_hi:[0,1]
	v_pk_add_f32 v[78:79], v[74:75], v[86:87] op_sel_hi:[1,0] neg_lo:[0,1] neg_hi:[0,1]
	v_pk_add_f32 v[74:75], v[70:71], v[86:87] op_sel_hi:[1,0] neg_lo:[0,1] neg_hi:[0,1]
	v_pk_mul_f32 v[68:69], v[86:87], v[76:77] op_sel:[1,0]
	v_pk_mul_f32 v[70:71], v[86:87], v[78:79] op_sel:[1,0]
	v_pk_mul_f32 v[72:73], v[86:87], v[72:73] op_sel:[1,0]
	v_pk_mul_f32 v[74:75], v[86:87], v[74:75] op_sel:[1,0]
	v_pk_fma_f32 v[68:69], v[140:141], v[68:69], v[144:145]
	v_pk_fma_f32 v[70:71], v[142:143], v[70:71], v[146:147]
	v_pk_fma_f32 v[72:73], v[132:133], v[72:73], v[136:137]
	v_pk_fma_f32 v[74:75], v[134:135], v[74:75], v[138:139]
	s_mov_b64 s[6:7], -1
	s_and_b64 vcc, exec, s[2:3]
	s_cbranch_vccz .LBB0_516
	v_cvt_pk_f16_f32 v76, v68, v69
	v_cvt_pk_f16_f32 v77, v70, v71
	v_cvt_pk_f16_f32 v78, v72, v73
	v_cvt_pk_f16_f32 v79, v74, v75
	v_add_u32_e32 v76, 0x20002, v76
	v_add_u32_e32 v77, 0x20002, v77
	v_add_u32_e32 v78, 0x20002, v78
	v_add_u32_e32 v79, 0x20002, v79
	v_and_b32_e32 v76, 0xfffcfffc, v76
	v_and_b32_e32 v77, 0xfffcfffc, v77
	v_and_b32_e32 v78, 0xfffcfffc, v78
	v_and_b32_e32 v79, 0xfffcfffc, v79
	s_and_b64 vcc, exec, s[16:17]
	global_store_dwordx4 v[88:89], v[76:79], off offset:256
	s_cbranch_vccnz .LBB0_515
	s_nop 0
	v_mov_b32_e32 v76, v33
	v_mov_b32_e32 v77, v33
	v_cvt_pk_fp8_f32 v76, v68, v69
	v_cvt_pk_fp8_f32 v77, v72, v73
	v_readlane_b32 s6, v252, 26
	v_readlane_b32 s7, v252, 27
	v_cvt_pk_fp8_f32 v76, v70, v71 op_sel:[0,0,1]
	v_cvt_pk_fp8_f32 v77, v74, v75 op_sel:[0,0,1]
	v_lshl_add_u64 v[78:79], s[6:7], 0, v[84:85]
	v_lshl_add_u64 v[78:79], v[78:79], 0, v[198:199]
	global_store_dwordx2 v[78:79], v[76:77], off offset:128

; template <unsigned D> __device__ __forceinline__ u32x4 rd8(u32x4 w) { w.x = rd<D>(w.x); w.y = rd<D>(w.y); w.z = rd<D>(w.z); w.w = rd<D>(w.w); return w; }
; __device__ __forceinline__ u32x4 pk8(const f32x4 v0, const f32x4 v1) { u32x4 w; w.x = pk_f16(v0[0], v0[1]); w.y = pk_f16(v0[2], v0[3]); w.z = pk_f16(v1[0], v1[1]); w.w = pk_f16(v1[2], v1[3]); return w; }
; __device__ __forceinline__ unsigned pk4_fp8(float a, float b, float c, float d) { int w = __builtin_amdgcn_cvt_pk_fp8_f32(a, b, 0, false); w = __builtin_amdgcn_cvt_pk_fp8_f32(c, d, w, true); return (unsigned)w; }
;     __device__ __forceinline__ void fused(f32x4 (&acc)[2][2][4][2], const GUnit& u, int wr, int wc, int fr, int fq, LAS unsigned char* lds, int wid, int lane) const {
;     ...
;             for (int m = 0; m < 4; ++m) { const int r = ai * 128 + wr * 64 + m * 16 + fr; const f32x2 sr = S[r]; const size_t row = (size_t)(u.pm * 256 + r);
; #pragma unroll
;                 for (int bj = 0; bj < 2; ++bj) { const int col = gcol0 + bj * 128;
;                     f32x4 y0 = (acc[ai][bj][m][0] - sr.x) * sr.y * gv[bj][0] + bv[bj][0], y1 = (acc[ai][bj][m][1] - sr.x) * sr.y * gv[bj][1] + bv[bj][1];
;                     if (bad) { y0 = (f32x4){qnan, qnan, qnan, qnan}; y1 = y0; }
;                     if (last) { *(f32x4*)(out + row * 1024 + col) = y0; *(f32x4*)(out + row * 1024 + col + 4) = y1; }
;                     else { *(u32x4*)(H16 + row * 1024 + col) = rd8<D_H>(pk8(y0, y1));
;                            if (h8out) { u32x2 q8v; q8v.x = pk4_fp8(y0[0], y0[1], y0[2], y0[3]); q8v.y = pk4_fp8(y1[0], y1[1], y1[2], y1[3]); *(u32x2*)(ws + WS_H8 + row * 1024 + col) = q8v; } } }
.LBB0_518:
	ds_read_b64 v[70:71], v32 offset:9216
	v_readlane_b32 s6, v253, 4
	v_readlane_b32 s7, v253, 5
	v_lshlrev_b64 v[68:69], 10, v[212:213]
	s_and_b64 vcc, exec, s[2:3]
	s_waitcnt lgkmcnt(0)
	v_cndmask_b32_e64 v71, v229, v71, s[100:101]
	v_pk_add_f32 v[74:75], v[64:65], v[70:71] op_sel_hi:[1,0] neg_lo:[0,1] neg_hi:[0,1]
	v_pk_add_f32 v[64:65], v[60:61], v[70:71] op_sel_hi:[1,0] neg_lo:[0,1] neg_hi:[0,1]
	v_pk_add_f32 v[76:77], v[66:67], v[70:71] op_sel_hi:[1,0] neg_lo:[0,1] neg_hi:[0,1]
	v_pk_add_f32 v[66:67], v[62:63], v[70:71] op_sel_hi:[1,0] neg_lo:[0,1] neg_hi:[0,1]
	v_pk_mul_f32 v[60:61], v[70:71], v[74:75] op_sel:[1,0]
	v_pk_mul_f32 v[62:63], v[70:71], v[76:77] op_sel:[1,0]
	v_pk_mul_f32 v[64:65], v[70:71], v[64:65] op_sel:[1,0]
	v_pk_mul_f32 v[66:67], v[70:71], v[66:67] op_sel:[1,0]
	v_lshl_add_u64 v[72:73], s[6:7], 0, v[210:211]
	v_pk_fma_f32 v[60:61], v[160:161], v[60:61], v[156:157]
	v_pk_fma_f32 v[62:63], v[162:163], v[62:63], v[158:159]
	v_pk_fma_f32 v[64:65], v[148:149], v[64:65], v[152:153]
	v_pk_fma_f32 v[66:67], v[150:151], v[66:67], v[154:155]
	s_mov_b64 s[6:7], -1
	v_lshl_add_u64 v[72:73], v[198:199], 1, v[72:73]
	s_cbranch_vccz .LBB0_522
	v_cvt_pk_f16_f32 v74, v60, v61
	v_cvt_pk_f16_f32 v75, v62, v63
	v_cvt_pk_f16_f32 v76, v64, v65
	v_cvt_pk_f16_f32 v77, v66, v67
	v_add_u32_e32 v74, 0x20002, v74
	v_add_u32_e32 v75, 0x20002, v75
	v_add_u32_e32 v76, 0x20002, v76
	v_add_u32_e32 v77, 0x20002, v77
	v_and_b32_e32 v74, 0xfffcfffc, v74
	v_and_b32_e32 v75, 0xfffcfffc, v75
	v_and_b32_e32 v76, 0xfffcfffc, v76
	v_and_b32_e32 v77, 0xfffcfffc, v77
	s_and_b64 vcc, exec, s[16:17]
	global_store_dwordx4 v[72:73], v[74:77], off
	s_cbranch_vccnz .LBB0_521
	s_nop 0
	v_mov_b32_e32 v74, v33
	v_mov_b32_e32 v75, v33
	v_cvt_pk_fp8_f32 v74, v60, v61
	v_cvt_pk_fp8_f32 v75, v64, v65
	v_readlane_b32 s6, v252, 26
	v_readlane_b32 s7, v252, 27
	v_cvt_pk_fp8_f32 v74, v62, v63 op_sel:[0,0,1]
	v_cvt_pk_fp8_f32 v75, v66, v67 op_sel:[0,0,1]
	v_lshl_add_u64 v[76:77], s[6:7], 0, v[68:69]
	v_lshl_add_u64 v[76:77], v[76:77], 0, v[198:199]
	global_store_dwordx2 v[76:77], v[74:75], off

; template <unsigned D> __device__ __forceinline__ u32x4 rd8(u32x4 w) { w.x = rd<D>(w.x); w.y = rd<D>(w.y); w.z = rd<D>(w.z); w.w = rd<D>(w.w); return w; }
; __device__ __forceinline__ u32x4 pk8(const f32x4 v0, const f32x4 v1) { u32x4 w; w.x = pk_f16(v0[0], v0[1]); w.y = pk_f16(v0[2], v0[3]); w.z = pk_f16(v1[0], v1[1]); w.w = pk_f16(v1[2], v1[3]); return w; }
; __device__ __forceinline__ unsigned pk4_fp8(float a, float b, float c, float d) { int w = __builtin_amdgcn_cvt_pk_fp8_f32(a, b, 0, false); w = __builtin_amdgcn_cvt_pk_fp8_f32(c, d, w, true); return (unsigned)w; }
;     __device__ __forceinline__ void fused(f32x4 (&acc)[2][2][4][2], const GUnit& u, int wr, int wc, int fr, int fq, LAS unsigned char* lds, int wid, int lane) const {
;     ...
;             for (int m = 0; m < 4; ++m) { const int r = ai * 128 + wr * 64 + m * 16 + fr; const f32x2 sr = S[r]; const size_t row = (size_t)(u.pm * 256 + r);
; #pragma unroll
;                 for (int bj = 0; bj < 2; ++bj) { const int col = gcol0 + bj * 128;
;                     f32x4 y0 = (acc[ai][bj][m][0] - sr.x) * sr.y * gv[bj][0] + bv[bj][0], y1 = (acc[ai][bj][m][1] - sr.x) * sr.y * gv[bj][1] + bv[bj][1];
;                     if (bad) { y0 = (f32x4){qnan, qnan, qnan, qnan}; y1 = y0; }
;                     if (last) { *(f32x4*)(out + row * 1024 + col) = y0; *(f32x4*)(out + row * 1024 + col + 4) = y1; }
;                     else { *(u32x4*)(H16 + row * 1024 + col) = rd8<D_H>(pk8(y0, y1));
;                            if (h8out) { u32x2 q8v; q8v.x = pk4_fp8(y0[0], y0[1], y0[2], y0[3]); q8v.y = pk4_fp8(y1[0], y1[1], y1[2], y1[3]); *(u32x2*)(ws + WS_H8 + row * 1024 + col) = q8v; } } }
.LBB0_524:
	s_nop 0
	v_pk_add_f32 v[60:61], v[56:57], v[70:71] op_sel_hi:[1,0] neg_lo:[0,1] neg_hi:[0,1]
	v_pk_add_f32 v[56:57], v[52:53], v[70:71] op_sel_hi:[1,0] neg_lo:[0,1] neg_hi:[0,1]
	v_pk_add_f32 v[62:63], v[58:59], v[70:71] op_sel_hi:[1,0] neg_lo:[0,1] neg_hi:[0,1]
	v_pk_add_f32 v[58:59], v[54:55], v[70:71] op_sel_hi:[1,0] neg_lo:[0,1] neg_hi:[0,1]
	v_pk_mul_f32 v[52:53], v[70:71], v[60:61] op_sel:[1,0]
	v_pk_mul_f32 v[54:55], v[70:71], v[62:63] op_sel:[1,0]
	v_pk_mul_f32 v[56:57], v[70:71], v[56:57] op_sel:[1,0]
	v_pk_mul_f32 v[58:59], v[70:71], v[58:59] op_sel:[1,0]
	v_pk_fma_f32 v[52:53], v[140:141], v[52:53], v[144:145]
	v_pk_fma_f32 v[54:55], v[142:143], v[54:55], v[146:147]
	v_pk_fma_f32 v[56:57], v[132:133], v[56:57], v[136:137]
	v_pk_fma_f32 v[58:59], v[134:135], v[58:59], v[138:139]
	s_mov_b64 s[6:7], -1
	s_and_b64 vcc, exec, s[2:3]
	s_cbranch_vccz .LBB0_528
	v_cvt_pk_f16_f32 v60, v52, v53
	v_cvt_pk_f16_f32 v61, v54, v55
	v_cvt_pk_f16_f32 v62, v56, v57
	v_cvt_pk_f16_f32 v63, v58, v59
	v_add_u32_e32 v60, 0x20002, v60
	v_add_u32_e32 v61, 0x20002, v61
	v_add_u32_e32 v62, 0x20002, v62
	v_add_u32_e32 v63, 0x20002, v63
	v_and_b32_e32 v60, 0xfffcfffc, v60
	v_and_b32_e32 v61, 0xfffcfffc, v61
	v_and_b32_e32 v62, 0xfffcfffc, v62
	v_and_b32_e32 v63, 0xfffcfffc, v63
	s_and_b64 vcc, exec, s[16:17]
	global_store_dwordx4 v[72:73], v[60:63], off offset:256
	s_cbranch_vccnz .LBB0_527
	s_nop 0
	v_mov_b32_e32 v60, v33
	v_mov_b32_e32 v61, v33
	v_cvt_pk_fp8_f32 v60, v52, v53
	v_cvt_pk_fp8_f32 v61, v56, v57
	v_readlane_b32 s6, v252, 26
	v_readlane_b32 s7, v252, 27
	v_cvt_pk_fp8_f32 v60, v54, v55 op_sel:[0,0,1]
	v_cvt_pk_fp8_f32 v61, v58, v59 op_sel:[0,0,1]
	v_lshl_add_u64 v[62:63], s[6:7], 0, v[68:69]
	v_lshl_add_u64 v[62:63], v[62:63], 0, v[198:199]
	global_store_dwordx2 v[62:63], v[60:61], off offset:128

; template <unsigned D> __device__ __forceinline__ u32x4 rd8(u32x4 w) { w.x = rd<D>(w.x); w.y = rd<D>(w.y); w.z = rd<D>(w.z); w.w = rd<D>(w.w); return w; }
; __device__ __forceinline__ u32x4 pk8(const f32x4 v0, const f32x4 v1) { u32x4 w; w.x = pk_f16(v0[0], v0[1]); w.y = pk_f16(v0[2], v0[3]); w.z = pk_f16(v1[0], v1[1]); w.w = pk_f16(v1[2], v1[3]); return w; }
; __device__ __forceinline__ unsigned pk4_fp8(float a, float b, float c, float d) { int w = __builtin_amdgcn_cvt_pk_fp8_f32(a, b, 0, false); w = __builtin_amdgcn_cvt_pk_fp8_f32(c, d, w, true); return (unsigned)w; }
;     __device__ __forceinline__ void fused(f32x4 (&acc)[2][2][4][2], const GUnit& u, int wr, int wc, int fr, int fq, LAS unsigned char* lds, int wid, int lane) const {
;     ...
;             for (int m = 0; m < 4; ++m) { const int r = ai * 128 + wr * 64 + m * 16 + fr; const f32x2 sr = S[r]; const size_t row = (size_t)(u.pm * 256 + r);
; #pragma unroll
;                 for (int bj = 0; bj < 2; ++bj) { const int col = gcol0 + bj * 128;
;                     f32x4 y0 = (acc[ai][bj][m][0] - sr.x) * sr.y * gv[bj][0] + bv[bj][0], y1 = (acc[ai][bj][m][1] - sr.x) * sr.y * gv[bj][1] + bv[bj][1];
;                     if (bad) { y0 = (f32x4){qnan, qnan, qnan, qnan}; y1 = y0; }
;                     if (last) { *(f32x4*)(out + row * 1024 + col) = y0; *(f32x4*)(out + row * 1024 + col + 4) = y1; }
;                     else { *(u32x4*)(H16 + row * 1024 + col) = rd8<D_H>(pk8(y0, y1));
;                            if (h8out) { u32x2 q8v; q8v.x = pk4_fp8(y0[0], y0[1], y0[2], y0[3]); q8v.y = pk4_fp8(y1[0], y1[1], y1[2], y1[3]); *(u32x2*)(ws + WS_H8 + row * 1024 + col) = q8v; } } }
.LBB0_530:
	ds_read_b64 v[54:55], v32 offset:9344
	v_readlane_b32 s6, v253, 4
	v_readlane_b32 s7, v253, 5
	v_lshlrev_b64 v[52:53], 10, v[208:209]
	s_and_b64 vcc, exec, s[2:3]
	s_waitcnt lgkmcnt(0)
	v_cndmask_b32_e64 v55, v229, v55, s[100:101]
	v_pk_add_f32 v[56:57], v[48:49], v[54:55] op_sel_hi:[1,0] neg_lo:[0,1] neg_hi:[0,1]
	v_pk_add_f32 v[48:49], v[44:45], v[54:55] op_sel_hi:[1,0] neg_lo:[0,1] neg_hi:[0,1]
	v_pk_add_f32 v[58:59], v[50:51], v[54:55] op_sel_hi:[1,0] neg_lo:[0,1] neg_hi:[0,1]
	v_pk_add_f32 v[50:51], v[46:47], v[54:55] op_sel_hi:[1,0] neg_lo:[0,1] neg_hi:[0,1]
	v_pk_mul_f32 v[44:45], v[54:55], v[56:57] op_sel:[1,0]
	v_pk_mul_f32 v[46:47], v[54:55], v[58:59] op_sel:[1,0]
	v_pk_mul_f32 v[48:49], v[54:55], v[48:49] op_sel:[1,0]
	v_pk_mul_f32 v[50:51], v[54:55], v[50:51] op_sel:[1,0]
	v_lshl_add_u64 v[34:35], s[6:7], 0, v[34:35]
	v_pk_fma_f32 v[44:45], v[160:161], v[44:45], v[156:157]
	v_pk_fma_f32 v[46:47], v[162:163], v[46:47], v[158:159]
	v_pk_fma_f32 v[48:49], v[148:149], v[48:49], v[152:153]
	v_pk_fma_f32 v[50:51], v[150:151], v[50:51], v[154:155]
	s_mov_b64 s[6:7], -1
	v_lshl_add_u64 v[56:57], v[198:199], 1, v[34:35]
	s_cbranch_vccz .LBB0_534
	v_cvt_pk_f16_f32 v34, v44, v45
	v_cvt_pk_f16_f32 v35, v46, v47
	v_add_u32_e32 v34, 0x20002, v34
	v_cvt_pk_f16_f32 v60, v48, v49
	v_and_b32_e32 v58, 0xfffcfffc, v34
	v_add_u32_e32 v34, 0x20002, v35
	v_cvt_pk_f16_f32 v61, v50, v51
	v_and_b32_e32 v59, 0xfffcfffc, v34
	v_add_u32_e32 v34, 0x20002, v60
	v_and_b32_e32 v60, 0xfffcfffc, v34
	v_add_u32_e32 v34, 0x20002, v61
	v_and_b32_e32 v61, 0xfffcfffc, v34
	s_and_b64 vcc, exec, s[16:17]
	global_store_dwordx4 v[56:57], v[58:61], off
	s_cbranch_vccnz .LBB0_533
	v_mov_b32_e32 v34, v33
	v_mov_b32_e32 v35, v33
	v_cvt_pk_fp8_f32 v34, v44, v45
	v_cvt_pk_fp8_f32 v35, v48, v49
	v_readlane_b32 s6, v252, 26
	v_readlane_b32 s7, v252, 27
	v_cvt_pk_fp8_f32 v34, v46, v47 op_sel:[0,0,1]
	v_cvt_pk_fp8_f32 v35, v50, v51 op_sel:[0,0,1]
	v_lshl_add_u64 v[58:59], s[6:7], 0, v[52:53]
	v_lshl_add_u64 v[58:59], v[58:59], 0, v[198:199]
	global_store_dwordx2 v[58:59], v[34:35], off

; template <unsigned D> __device__ __forceinline__ u32x4 rd8(u32x4 w) { w.x = rd<D>(w.x); w.y = rd<D>(w.y); w.z = rd<D>(w.z); w.w = rd<D>(w.w); return w; }
; __device__ __forceinline__ u32x4 pk8(const f32x4 v0, const f32x4 v1) { u32x4 w; w.x = pk_f16(v0[0], v0[1]); w.y = pk_f16(v0[2], v0[3]); w.z = pk_f16(v1[0], v1[1]); w.w = pk_f16(v1[2], v1[3]); return w; }
; __device__ __forceinline__ unsigned pk4_fp8(float a, float b, float c, float d) { int w = __builtin_amdgcn_cvt_pk_fp8_f32(a, b, 0, false); w = __builtin_amdgcn_cvt_pk_fp8_f32(c, d, w, true); return (unsigned)w; }
;     __device__ __forceinline__ void fused(f32x4 (&acc)[2][2][4][2], const GUnit& u, int wr, int wc, int fr, int fq, LAS unsigned char* lds, int wid, int lane) const {
;     ...
;             for (int m = 0; m < 4; ++m) { const int r = ai * 128 + wr * 64 + m * 16 + fr; const f32x2 sr = S[r]; const size_t row = (size_t)(u.pm * 256 + r);
; #pragma unroll
;                 for (int bj = 0; bj < 2; ++bj) { const int col = gcol0 + bj * 128;
;                     f32x4 y0 = (acc[ai][bj][m][0] - sr.x) * sr.y * gv[bj][0] + bv[bj][0], y1 = (acc[ai][bj][m][1] - sr.x) * sr.y * gv[bj][1] + bv[bj][1];
;                     if (bad) { y0 = (f32x4){qnan, qnan, qnan, qnan}; y1 = y0; }
;                     if (last) { *(f32x4*)(out + row * 1024 + col) = y0; *(f32x4*)(out + row * 1024 + col + 4) = y1; }
;                     else { *(u32x4*)(H16 + row * 1024 + col) = rd8<D_H>(pk8(y0, y1));
;                            if (h8out) { u32x2 q8v; q8v.x = pk4_fp8(y0[0], y0[1], y0[2], y0[3]); q8v.y = pk4_fp8(y1[0], y1[1], y1[2], y1[3]); *(u32x2*)(ws + WS_H8 + row * 1024 + col) = q8v; } } }
.LBB0_536:
	v_pk_add_f32 v[34:35], v[40:41], v[54:55] op_sel_hi:[1,0] neg_lo:[0,1] neg_hi:[0,1]
	v_pk_add_f32 v[40:41], v[38:39], v[54:55] op_sel_hi:[1,0] neg_lo:[0,1] neg_hi:[0,1]
	v_pk_add_f32 v[38:39], v[36:37], v[54:55] op_sel_hi:[1,0] neg_lo:[0,1] neg_hi:[0,1]
	v_pk_add_f32 v[36:37], v[42:43], v[54:55] op_sel_hi:[1,0] neg_lo:[0,1] neg_hi:[0,1]
	v_pk_mul_f32 v[34:35], v[54:55], v[34:35] op_sel:[1,0]
	v_pk_mul_f32 v[36:37], v[54:55], v[36:37] op_sel:[1,0]
	v_pk_mul_f32 v[38:39], v[54:55], v[38:39] op_sel:[1,0]
	v_pk_mul_f32 v[40:41], v[54:55], v[40:41] op_sel:[1,0]
	v_pk_fma_f32 v[34:35], v[140:141], v[34:35], v[144:145]
	v_pk_fma_f32 v[36:37], v[142:143], v[36:37], v[146:147]
	v_pk_fma_f32 v[38:39], v[132:133], v[38:39], v[136:137]
	v_pk_fma_f32 v[40:41], v[134:135], v[40:41], v[138:139]
	s_mov_b64 s[6:7], -1
	s_and_b64 vcc, exec, s[2:3]
	s_cbranch_vccz .LBB0_540
	v_cvt_pk_f16_f32 v42, v34, v35
	v_cvt_pk_f16_f32 v43, v36, v37
	v_cvt_pk_f16_f32 v44, v38, v39
	v_cvt_pk_f16_f32 v45, v40, v41
	v_add_u32_e32 v42, 0x20002, v42
	v_add_u32_e32 v43, 0x20002, v43
	v_add_u32_e32 v44, 0x20002, v44
	v_add_u32_e32 v45, 0x20002, v45
	v_and_b32_e32 v42, 0xfffcfffc, v42
	v_and_b32_e32 v43, 0xfffcfffc, v43
	v_and_b32_e32 v44, 0xfffcfffc, v44
	v_and_b32_e32 v45, 0xfffcfffc, v45
	s_and_b64 vcc, exec, s[16:17]
	global_store_dwordx4 v[56:57], v[42:45], off offset:256
	s_cbranch_vccnz .LBB0_539
	s_nop 0
	v_mov_b32_e32 v42, v33
	v_mov_b32_e32 v43, v33
	v_cvt_pk_fp8_f32 v42, v34, v35
	v_cvt_pk_fp8_f32 v43, v38, v39
	v_readlane_b32 s6, v252, 26
	v_readlane_b32 s7, v252, 27
	v_cvt_pk_fp8_f32 v42, v36, v37 op_sel:[0,0,1]
	v_cvt_pk_fp8_f32 v43, v40, v41 op_sel:[0,0,1]
	v_lshl_add_u64 v[44:45], s[6:7], 0, v[52:53]
	v_lshl_add_u64 v[44:45], v[44:45], 0, v[198:199]
	global_store_dwordx2 v[44:45], v[42:43], off offset:128

; template <unsigned D> __device__ __forceinline__ u32x4 rd8(u32x4 w) { w.x = rd<D>(w.x); w.y = rd<D>(w.y); w.z = rd<D>(w.z); w.w = rd<D>(w.w); return w; }
; __device__ __forceinline__ u32x4 pk8(const f32x4 v0, const f32x4 v1) { u32x4 w; w.x = pk_f16(v0[0], v0[1]); w.y = pk_f16(v0[2], v0[3]); w.z = pk_f16(v1[0], v1[1]); w.w = pk_f16(v1[2], v1[3]); return w; }
; __device__ __forceinline__ unsigned pk4_fp8(float a, float b, float c, float d) { int w = __builtin_amdgcn_cvt_pk_fp8_f32(a, b, 0, false); w = __builtin_amdgcn_cvt_pk_fp8_f32(c, d, w, true); return (unsigned)w; }
;     __device__ __forceinline__ void fused(f32x4 (&acc)[2][2][4][2], const GUnit& u, int wr, int wc, int fr, int fq, LAS unsigned char* lds, int wid, int lane) const {
;     ...
;             for (int m = 0; m < 4; ++m) { const int r = ai * 128 + wr * 64 + m * 16 + fr; const f32x2 sr = S[r]; const size_t row = (size_t)(u.pm * 256 + r);
; #pragma unroll
;                 for (int bj = 0; bj < 2; ++bj) { const int col = gcol0 + bj * 128;
;                     f32x4 y0 = (acc[ai][bj][m][0] - sr.x) * sr.y * gv[bj][0] + bv[bj][0], y1 = (acc[ai][bj][m][1] - sr.x) * sr.y * gv[bj][1] + bv[bj][1];
;                     if (bad) { y0 = (f32x4){qnan, qnan, qnan, qnan}; y1 = y0; }
;                     if (last) { *(f32x4*)(out + row * 1024 + col) = y0; *(f32x4*)(out + row * 1024 + col + 4) = y1; }
;                     else { *(u32x4*)(H16 + row * 1024 + col) = rd8<D_H>(pk8(y0, y1));
;                            if (h8out) { u32x2 q8v; q8v.x = pk4_fp8(y0[0], y0[1], y0[2], y0[3]); q8v.y = pk4_fp8(y1[0], y1[1], y1[2], y1[3]); *(u32x2*)(ws + WS_H8 + row * 1024 + col) = q8v; } } }
.LBB0_542:
	ds_read_b64 v[36:37], v32 offset:9472
	v_readlane_b32 s6, v253, 4
	v_readlane_b32 s7, v253, 5
	v_lshlrev_b64 v[34:35], 10, v[206:207]
	s_and_b64 vcc, exec, s[2:3]
	s_waitcnt lgkmcnt(0)
	v_cndmask_b32_e64 v37, v229, v37, s[100:101]
	v_pk_add_f32 v[40:41], v[28:29], v[36:37] op_sel_hi:[1,0] neg_lo:[0,1] neg_hi:[0,1]
	v_pk_add_f32 v[28:29], v[24:25], v[36:37] op_sel_hi:[1,0] neg_lo:[0,1] neg_hi:[0,1]
	v_pk_add_f32 v[42:43], v[30:31], v[36:37] op_sel_hi:[1,0] neg_lo:[0,1] neg_hi:[0,1]
	v_pk_add_f32 v[30:31], v[26:27], v[36:37] op_sel_hi:[1,0] neg_lo:[0,1] neg_hi:[0,1]
	v_pk_mul_f32 v[24:25], v[36:37], v[40:41] op_sel:[1,0]
	v_pk_mul_f32 v[26:27], v[36:37], v[42:43] op_sel:[1,0]
	v_pk_mul_f32 v[28:29], v[36:37], v[28:29] op_sel:[1,0]
	v_pk_mul_f32 v[30:31], v[36:37], v[30:31] op_sel:[1,0]
	v_lshl_add_u64 v[38:39], s[6:7], 0, v[204:205]
	v_pk_fma_f32 v[24:25], v[160:161], v[24:25], v[156:157]
	v_pk_fma_f32 v[26:27], v[162:163], v[26:27], v[158:159]
	v_pk_fma_f32 v[28:29], v[148:149], v[28:29], v[152:153]
	v_pk_fma_f32 v[30:31], v[150:151], v[30:31], v[154:155]
	s_mov_b64 s[6:7], -1
	v_lshl_add_u64 v[38:39], v[198:199], 1, v[38:39]
	s_cbranch_vccz .LBB0_546
	v_cvt_pk_f16_f32 v40, v24, v25
	v_cvt_pk_f16_f32 v41, v26, v27
	v_cvt_pk_f16_f32 v42, v28, v29
	v_cvt_pk_f16_f32 v43, v30, v31
	v_add_u32_e32 v40, 0x20002, v40
	v_add_u32_e32 v41, 0x20002, v41
	v_add_u32_e32 v42, 0x20002, v42
	v_add_u32_e32 v43, 0x20002, v43
	v_and_b32_e32 v40, 0xfffcfffc, v40
	v_and_b32_e32 v41, 0xfffcfffc, v41
	v_and_b32_e32 v42, 0xfffcfffc, v42
	v_and_b32_e32 v43, 0xfffcfffc, v43
	s_and_b64 vcc, exec, s[16:17]
	global_store_dwordx4 v[38:39], v[40:43], off
	s_cbranch_vccnz .LBB0_545
	s_nop 0
	v_mov_b32_e32 v40, v33
	v_mov_b32_e32 v41, v33
	v_cvt_pk_fp8_f32 v40, v24, v25
	v_cvt_pk_fp8_f32 v41, v28, v29
	v_readlane_b32 s6, v252, 26
	v_readlane_b32 s7, v252, 27
	v_cvt_pk_fp8_f32 v40, v26, v27 op_sel:[0,0,1]
	v_cvt_pk_fp8_f32 v41, v30, v31 op_sel:[0,0,1]
	v_lshl_add_u64 v[42:43], s[6:7], 0, v[34:35]
	v_lshl_add_u64 v[42:43], v[42:43], 0, v[198:199]
	global_store_dwordx2 v[42:43], v[40:41], off

; template <unsigned D> __device__ __forceinline__ u32x4 rd8(u32x4 w) { w.x = rd<D>(w.x); w.y = rd<D>(w.y); w.z = rd<D>(w.z); w.w = rd<D>(w.w); return w; }
; __device__ __forceinline__ u32x4 pk8(const f32x4 v0, const f32x4 v1) { u32x4 w; w.x = pk_f16(v0[0], v0[1]); w.y = pk_f16(v0[2], v0[3]); w.z = pk_f16(v1[0], v1[1]); w.w = pk_f16(v1[2], v1[3]); return w; }
; __device__ __forceinline__ unsigned pk4_fp8(float a, float b, float c, float d) { int w = __builtin_amdgcn_cvt_pk_fp8_f32(a, b, 0, false); w = __builtin_amdgcn_cvt_pk_fp8_f32(c, d, w, true); return (unsigned)w; }
;     __device__ __forceinline__ void fused(f32x4 (&acc)[2][2][4][2], const GUnit& u, int wr, int wc, int fr, int fq, LAS unsigned char* lds, int wid, int lane) const {
;     ...
;             for (int m = 0; m < 4; ++m) { const int r = ai * 128 + wr * 64 + m * 16 + fr; const f32x2 sr = S[r]; const size_t row = (size_t)(u.pm * 256 + r);
; #pragma unroll
;                 for (int bj = 0; bj < 2; ++bj) { const int col = gcol0 + bj * 128;
;                     f32x4 y0 = (acc[ai][bj][m][0] - sr.x) * sr.y * gv[bj][0] + bv[bj][0], y1 = (acc[ai][bj][m][1] - sr.x) * sr.y * gv[bj][1] + bv[bj][1];
;                     if (bad) { y0 = (f32x4){qnan, qnan, qnan, qnan}; y1 = y0; }
;                     if (last) { *(f32x4*)(out + row * 1024 + col) = y0; *(f32x4*)(out + row * 1024 + col + 4) = y1; }
;                     else { *(u32x4*)(H16 + row * 1024 + col) = rd8<D_H>(pk8(y0, y1));
;                            if (h8out) { u32x2 q8v; q8v.x = pk4_fp8(y0[0], y0[1], y0[2], y0[3]); q8v.y = pk4_fp8(y1[0], y1[1], y1[2], y1[3]); *(u32x2*)(ws + WS_H8 + row * 1024 + col) = q8v; } } }
.LBB0_548:
	s_nop 0
	v_pk_add_f32 v[24:25], v[20:21], v[36:37] op_sel_hi:[1,0] neg_lo:[0,1] neg_hi:[0,1]
	v_pk_add_f32 v[20:21], v[16:17], v[36:37] op_sel_hi:[1,0] neg_lo:[0,1] neg_hi:[0,1]
	v_pk_add_f32 v[26:27], v[22:23], v[36:37] op_sel_hi:[1,0] neg_lo:[0,1] neg_hi:[0,1]
	v_pk_add_f32 v[22:23], v[18:19], v[36:37] op_sel_hi:[1,0] neg_lo:[0,1] neg_hi:[0,1]
	v_pk_mul_f32 v[16:17], v[36:37], v[24:25] op_sel:[1,0]
	v_pk_mul_f32 v[18:19], v[36:37], v[26:27] op_sel:[1,0]
	v_pk_mul_f32 v[20:21], v[36:37], v[20:21] op_sel:[1,0]
	v_pk_mul_f32 v[22:23], v[36:37], v[22:23] op_sel:[1,0]
	v_pk_fma_f32 v[16:17], v[140:141], v[16:17], v[144:145]
	v_pk_fma_f32 v[18:19], v[142:143], v[18:19], v[146:147]
	v_pk_fma_f32 v[20:21], v[132:133], v[20:21], v[136:137]
	v_pk_fma_f32 v[22:23], v[134:135], v[22:23], v[138:139]
	s_mov_b64 s[6:7], -1
	s_and_b64 vcc, exec, s[2:3]
	s_cbranch_vccz .LBB0_552
	v_cvt_pk_f16_f32 v24, v16, v17
	v_cvt_pk_f16_f32 v25, v18, v19
	v_cvt_pk_f16_f32 v26, v20, v21
	v_cvt_pk_f16_f32 v27, v22, v23
	v_add_u32_e32 v24, 0x20002, v24
	v_add_u32_e32 v25, 0x20002, v25
	v_add_u32_e32 v26, 0x20002, v26
	v_add_u32_e32 v27, 0x20002, v27
	v_and_b32_e32 v24, 0xfffcfffc, v24
	v_and_b32_e32 v25, 0xfffcfffc, v25
	v_and_b32_e32 v26, 0xfffcfffc, v26
	v_and_b32_e32 v27, 0xfffcfffc, v27
	s_and_b64 vcc, exec, s[16:17]
	global_store_dwordx4 v[38:39], v[24:27], off offset:256
	s_cbranch_vccnz .LBB0_551
	s_nop 0
	v_mov_b32_e32 v24, v33
	v_mov_b32_e32 v25, v33
	v_cvt_pk_fp8_f32 v24, v16, v17
	v_cvt_pk_fp8_f32 v25, v20, v21
	v_readlane_b32 s6, v252, 26
	v_readlane_b32 s7, v252, 27
	v_cvt_pk_fp8_f32 v24, v18, v19 op_sel:[0,0,1]
	v_cvt_pk_fp8_f32 v25, v22, v23 op_sel:[0,0,1]
	v_lshl_add_u64 v[26:27], s[6:7], 0, v[34:35]
	v_lshl_add_u64 v[26:27], v[26:27], 0, v[198:199]
	global_store_dwordx2 v[26:27], v[24:25], off offset:128

; template <unsigned D> __device__ __forceinline__ u32x4 rd8(u32x4 w) { w.x = rd<D>(w.x); w.y = rd<D>(w.y); w.z = rd<D>(w.z); w.w = rd<D>(w.w); return w; }
; __device__ __forceinline__ u32x4 pk8(const f32x4 v0, const f32x4 v1) { u32x4 w; w.x = pk_f16(v0[0], v0[1]); w.y = pk_f16(v0[2], v0[3]); w.z = pk_f16(v1[0], v1[1]); w.w = pk_f16(v1[2], v1[3]); return w; }
; __device__ __forceinline__ unsigned pk4_fp8(float a, float b, float c, float d) { int w = __builtin_amdgcn_cvt_pk_fp8_f32(a, b, 0, false); w = __builtin_amdgcn_cvt_pk_fp8_f32(c, d, w, true); return (unsigned)w; }
;     __device__ __forceinline__ void fused(f32x4 (&acc)[2][2][4][2], const GUnit& u, int wr, int wc, int fr, int fq, LAS unsigned char* lds, int wid, int lane) const {
;     ...
;             for (int m = 0; m < 4; ++m) { const int r = ai * 128 + wr * 64 + m * 16 + fr; const f32x2 sr = S[r]; const size_t row = (size_t)(u.pm * 256 + r);
; #pragma unroll
;                 for (int bj = 0; bj < 2; ++bj) { const int col = gcol0 + bj * 128;
;                     f32x4 y0 = (acc[ai][bj][m][0] - sr.x) * sr.y * gv[bj][0] + bv[bj][0], y1 = (acc[ai][bj][m][1] - sr.x) * sr.y * gv[bj][1] + bv[bj][1];
;                     if (bad) { y0 = (f32x4){qnan, qnan, qnan, qnan}; y1 = y0; }
;                     if (last) { *(f32x4*)(out + row * 1024 + col) = y0; *(f32x4*)(out + row * 1024 + col + 4) = y1; }
;                     else { *(u32x4*)(H16 + row * 1024 + col) = rd8<D_H>(pk8(y0, y1));
;                            if (h8out) { u32x2 q8v; q8v.x = pk4_fp8(y0[0], y0[1], y0[2], y0[3]); q8v.y = pk4_fp8(y1[0], y1[1], y1[2], y1[3]); *(u32x2*)(ws + WS_H8 + row * 1024 + col) = q8v; } } }
.LBB0_554:
	ds_read_b64 v[18:19], v32 offset:9600
	v_readlane_b32 s6, v253, 4
	v_readlane_b32 s7, v253, 5
	v_lshlrev_b64 v[16:17], 10, v[200:201]
	s_and_b64 vcc, exec, s[2:3]
	s_waitcnt lgkmcnt(0)
	v_cndmask_b32_e64 v19, v229, v19, s[100:101]
	v_pk_add_f32 v[22:23], v[12:13], v[18:19] op_sel_hi:[1,0] neg_lo:[0,1] neg_hi:[0,1]
	v_pk_add_f32 v[12:13], v[8:9], v[18:19] op_sel_hi:[1,0] neg_lo:[0,1] neg_hi:[0,1]
	v_pk_add_f32 v[24:25], v[14:15], v[18:19] op_sel_hi:[1,0] neg_lo:[0,1] neg_hi:[0,1]
	v_pk_add_f32 v[14:15], v[10:11], v[18:19] op_sel_hi:[1,0] neg_lo:[0,1] neg_hi:[0,1]
	v_pk_mul_f32 v[8:9], v[18:19], v[22:23] op_sel:[1,0]
	v_pk_mul_f32 v[10:11], v[18:19], v[24:25] op_sel:[1,0]
	v_pk_mul_f32 v[12:13], v[18:19], v[12:13] op_sel:[1,0]
	v_pk_mul_f32 v[14:15], v[18:19], v[14:15] op_sel:[1,0]
	v_lshl_add_u64 v[20:21], s[6:7], 0, v[202:203]
	v_pk_fma_f32 v[8:9], v[160:161], v[8:9], v[156:157]
	v_pk_fma_f32 v[10:11], v[162:163], v[10:11], v[158:159]
	v_pk_fma_f32 v[12:13], v[148:149], v[12:13], v[152:153]
	v_pk_fma_f32 v[14:15], v[150:151], v[14:15], v[154:155]
	s_mov_b64 s[6:7], -1
	v_lshl_add_u64 v[20:21], v[198:199], 1, v[20:21]
	s_cbranch_vccz .LBB0_558
	v_cvt_pk_f16_f32 v22, v8, v9
	v_cvt_pk_f16_f32 v23, v10, v11
	v_cvt_pk_f16_f32 v24, v12, v13
	v_cvt_pk_f16_f32 v25, v14, v15
	v_add_u32_e32 v22, 0x20002, v22
	v_add_u32_e32 v23, 0x20002, v23
	v_add_u32_e32 v24, 0x20002, v24
	v_add_u32_e32 v25, 0x20002, v25
	v_and_b32_e32 v22, 0xfffcfffc, v22
	v_and_b32_e32 v23, 0xfffcfffc, v23
	v_and_b32_e32 v24, 0xfffcfffc, v24
	v_and_b32_e32 v25, 0xfffcfffc, v25
	s_and_b64 vcc, exec, s[16:17]
	global_store_dwordx4 v[20:21], v[22:25], off
	s_cbranch_vccnz .LBB0_557
	s_nop 0
	v_mov_b32_e32 v22, v33
	v_mov_b32_e32 v23, v33
	v_cvt_pk_fp8_f32 v22, v8, v9
	v_cvt_pk_fp8_f32 v23, v12, v13
	v_readlane_b32 s6, v252, 26
	v_readlane_b32 s7, v252, 27
	v_cvt_pk_fp8_f32 v22, v10, v11 op_sel:[0,0,1]
	v_cvt_pk_fp8_f32 v23, v14, v15 op_sel:[0,0,1]
	v_lshl_add_u64 v[24:25], s[6:7], 0, v[16:17]
	v_lshl_add_u64 v[24:25], v[24:25], 0, v[198:199]
	global_store_dwordx2 v[24:25], v[22:23], off

; template <unsigned D> __device__ __forceinline__ u32x4 rd8(u32x4 w) { w.x = rd<D>(w.x); w.y = rd<D>(w.y); w.z = rd<D>(w.z); w.w = rd<D>(w.w); return w; }
; __device__ __forceinline__ u32x4 pk8(const f32x4 v0, const f32x4 v1) { u32x4 w; w.x = pk_f16(v0[0], v0[1]); w.y = pk_f16(v0[2], v0[3]); w.z = pk_f16(v1[0], v1[1]); w.w = pk_f16(v1[2], v1[3]); return w; }
; __device__ __forceinline__ unsigned pk4_fp8(float a, float b, float c, float d) { int w = __builtin_amdgcn_cvt_pk_fp8_f32(a, b, 0, false); w = __builtin_amdgcn_cvt_pk_fp8_f32(c, d, w, true); return (unsigned)w; }
;     __device__ __forceinline__ void fused(f32x4 (&acc)[2][2][4][2], const GUnit& u, int wr, int wc, int fr, int fq, LAS unsigned char* lds, int wid, int lane) const {
;     ...
;             for (int m = 0; m < 4; ++m) { const int r = ai * 128 + wr * 64 + m * 16 + fr; const f32x2 sr = S[r]; const size_t row = (size_t)(u.pm * 256 + r);
; #pragma unroll
;                 for (int bj = 0; bj < 2; ++bj) { const int col = gcol0 + bj * 128;
;                     f32x4 y0 = (acc[ai][bj][m][0] - sr.x) * sr.y * gv[bj][0] + bv[bj][0], y1 = (acc[ai][bj][m][1] - sr.x) * sr.y * gv[bj][1] + bv[bj][1];
;                     if (bad) { y0 = (f32x4){qnan, qnan, qnan, qnan}; y1 = y0; }
;                     if (last) { *(f32x4*)(out + row * 1024 + col) = y0; *(f32x4*)(out + row * 1024 + col + 4) = y1; }
;                     else { *(u32x4*)(H16 + row * 1024 + col) = rd8<D_H>(pk8(y0, y1));
;                            if (h8out) { u32x2 q8v; q8v.x = pk4_fp8(y0[0], y0[1], y0[2], y0[3]); q8v.y = pk4_fp8(y1[0], y1[1], y1[2], y1[3]); *(u32x2*)(ws + WS_H8 + row * 1024 + col) = q8v; } } }
.LBB0_560:
	s_nop 0
	v_pk_add_f32 v[8:9], v[4:5], v[18:19] op_sel_hi:[1,0] neg_lo:[0,1] neg_hi:[0,1]
	v_pk_add_f32 v[4:5], v[0:1], v[18:19] op_sel_hi:[1,0] neg_lo:[0,1] neg_hi:[0,1]
	v_pk_add_f32 v[10:11], v[6:7], v[18:19] op_sel_hi:[1,0] neg_lo:[0,1] neg_hi:[0,1]
	v_pk_add_f32 v[6:7], v[2:3], v[18:19] op_sel_hi:[1,0] neg_lo:[0,1] neg_hi:[0,1]
	v_pk_mul_f32 v[0:1], v[18:19], v[8:9] op_sel:[1,0]
	v_pk_mul_f32 v[2:3], v[18:19], v[10:11] op_sel:[1,0]
	v_pk_mul_f32 v[4:5], v[18:19], v[4:5] op_sel:[1,0]
	v_pk_mul_f32 v[6:7], v[18:19], v[6:7] op_sel:[1,0]
	v_pk_fma_f32 v[0:1], v[140:141], v[0:1], v[144:145]
	v_pk_fma_f32 v[2:3], v[142:143], v[2:3], v[146:147]
	v_pk_fma_f32 v[4:5], v[132:133], v[4:5], v[136:137]
	v_pk_fma_f32 v[6:7], v[134:135], v[6:7], v[138:139]
	s_mov_b64 s[4:5], -1
	s_and_b64 vcc, exec, s[2:3]
	s_cbranch_vccz .LBB0_564
	v_cvt_pk_f16_f32 v8, v0, v1
	v_cvt_pk_f16_f32 v9, v2, v3
	v_cvt_pk_f16_f32 v10, v4, v5
	v_cvt_pk_f16_f32 v11, v6, v7
	v_add_u32_e32 v8, 0x20002, v8
	v_add_u32_e32 v9, 0x20002, v9
	v_add_u32_e32 v10, 0x20002, v10
	v_add_u32_e32 v11, 0x20002, v11
	v_and_b32_e32 v8, 0xfffcfffc, v8
	v_and_b32_e32 v9, 0xfffcfffc, v9
	v_and_b32_e32 v10, 0xfffcfffc, v10
	v_and_b32_e32 v11, 0xfffcfffc, v11
	s_and_b64 vcc, exec, s[16:17]
	global_store_dwordx4 v[20:21], v[8:11], off offset:256
	s_cbranch_vccnz .LBB0_563
	s_nop 0
	v_mov_b32_e32 v8, v33
	v_mov_b32_e32 v9, v33
	v_cvt_pk_fp8_f32 v8, v0, v1
	v_cvt_pk_fp8_f32 v9, v4, v5
	v_readlane_b32 s2, v252, 26
	v_readlane_b32 s3, v252, 27
	v_cvt_pk_fp8_f32 v8, v2, v3 op_sel:[0,0,1]
	v_cvt_pk_fp8_f32 v9, v6, v7 op_sel:[0,0,1]
	v_lshl_add_u64 v[10:11], s[2:3], 0, v[16:17]
	v_lshl_add_u64 v[10:11], v[10:11], 0, v[198:199]
	global_store_dwordx2 v[10:11], v[8:9], off offset:128
